# attention steady loop: loop bookkeeping (tile counter, ring-slot rotation, next V read base) rotated in front of the step-closing barrier
# baseline (speedup 1.0000x reference)
.LBB0_301:
	v_exp_f32_e32 v144, v144
	v_exp_f32_e32 v145, v145
	ds_read_b64_tr_b16 v[2:3], v0 offset:32768
	ds_read_b64_tr_b16 v[4:5], v0 offset:33280
	v_exp_f32_e32 v146, v146
	v_exp_f32_e32 v147, v147
	ds_read_b64_tr_b16 v[6:7], v0 offset:36864
	ds_read_b64_tr_b16 v[8:9], v0 offset:37376
	s_lshl_b32 s0, s19, 1
	s_add_i32 s0, s0, s47
	s_mov_b32 s1, m0
	s_mov_b32 m0, s0
	s_nop 0
	global_load_lds_dwordx4 v255, s[100:101]
	s_mov_b32 m0, s1
	v_exp_f32_e32 v148, v148
	v_exp_f32_e32 v149, v149
	ds_read_b64_tr_b16 v[10:11], v0 offset:33792
	ds_read_b64_tr_b16 v[12:13], v0 offset:34304
	s_addk_i32 s0, 0x1f80
	s_mov_b32 s1, m0
	s_mov_b32 m0, s0
	s_nop 0
	global_load_lds_dwordx4 v255, s[100:101] offset:128
	s_mov_b32 m0, s1
	s_add_u32 s98, s98, 0x20000
	s_addc_u32 s99, s99, 0
	s_add_u32 s100, s100, 0x20000
	s_addc_u32 s101, s101, 0
	s_waitcnt lgkmcnt(14)
	v_mfma_f32_32x32x16_bf16 v[32:47], v[172:175], v[112:115], v[32:47]
	v_exp_f32_e32 v150, v150
	v_exp_f32_e32 v151, v151
	ds_read_b64_tr_b16 v[108:109], v0 offset:37888
	ds_read_b64_tr_b16 v[110:111], v0 offset:38400
	s_waitcnt lgkmcnt(14)
	v_mfma_f32_32x32x16_bf16 v[16:31], v[164:167], v[116:119], v[16:31]
	v_exp_f32_e32 v152, v152
	v_exp_f32_e32 v153, v153
	ds_read_b64_tr_b16 v[112:113], v0 offset:34816
	ds_read_b64_tr_b16 v[114:115], v0 offset:35328
	s_waitcnt lgkmcnt(14)
	v_mfma_f32_32x32x16_bf16 v[32:47], v[164:167], v[96:99], v[32:47]
	v_exp_f32_e32 v154, v154
	v_exp_f32_e32 v155, v155
	ds_read_b64_tr_b16 v[116:117], v0 offset:38912
	ds_read_b64_tr_b16 v[118:119], v0 offset:39424
	s_waitcnt lgkmcnt(14)
	v_mfma_f32_32x32x16_bf16 v[16:31], v[160:163], v[100:103], v[16:31]
	v_exp_f32_e32 v156, v156
	v_exp_f32_e32 v157, v157
	ds_read_b64_tr_b16 v[100:101], v0 offset:35840
	ds_read_b64_tr_b16 v[102:103], v0 offset:36352
	s_waitcnt lgkmcnt(14)
	v_mfma_f32_32x32x16_bf16 v[32:47], v[160:163], v[104:107], v[32:47]
	v_exp_f32_e32 v158, v158
	v_exp_f32_e32 v159, v159
	ds_read_b64_tr_b16 v[104:105], v0 offset:39936
	ds_read_b64_tr_b16 v[106:107], v0 offset:40448
	s_waitcnt lgkmcnt(14)
	v_mfma_f32_32x32x16_bf16 v[48:63], v[180:183], v[2:5], v[48:63]
	v_exp_f32_e32 v128, v128
	v_exp_f32_e32 v129, v129
	s_waitcnt lgkmcnt(12)
	v_mfma_f32_32x32x16_bf16 v[64:79], v[180:183], v[6:9], v[64:79]
	v_exp_f32_e32 v130, v130
	v_exp_f32_e32 v131, v131
	v_add_u32_e32 v0, s19, v247
	ds_read_b128 v[96:99], v0
	ds_read_b128 v[204:207], v0 offset:512
	s_waitcnt lgkmcnt(12)
	v_mfma_f32_32x32x16_bf16 v[48:63], v[172:175], v[10:13], v[48:63]
	v_exp_f32_e32 v132, v132
	v_exp_f32_e32 v133, v133
	ds_read_b128 v[208:211], v0 offset:2048
	ds_read_b128 v[200:203], v0 offset:2560
	s_waitcnt lgkmcnt(12)
	v_mfma_f32_32x32x16_bf16 v[64:79], v[172:175], v[108:111], v[64:79]
	v_exp_f32_e32 v134, v134
	v_exp_f32_e32 v135, v135
	ds_read_b128 v[196:199], v0 offset:4096
	ds_read_b128 v[10:13], v0 offset:4608
	s_waitcnt lgkmcnt(12)
	v_mfma_f32_32x32x16_bf16 v[48:63], v[164:167], v[112:115], v[48:63]
	v_exp_f32_e32 v136, v136
	v_exp_f32_e32 v137, v137
	ds_read_b128 v[6:9], v0 offset:6144
	ds_read_b128 v[2:5], v0 offset:6656
	s_waitcnt lgkmcnt(12)
	v_mfma_f32_32x32x16_bf16 v[64:79], v[164:167], v[116:119], v[64:79]
	v_exp_f32_e32 v138, v138
	v_exp_f32_e32 v139, v139
	s_waitcnt lgkmcnt(10)
	v_mfma_f32_32x32x16_bf16 v[48:63], v[160:163], v[100:103], v[48:63]
	v_exp_f32_e32 v140, v140
	v_exp_f32_e32 v141, v141
	s_waitcnt lgkmcnt(8)
	v_mfma_f32_32x32x16_bf16 v[64:79], v[160:163], v[104:107], v[64:79]
	v_exp_f32_e32 v142, v142
	v_exp_f32_e32 v143, v143
	s_add_i32 s0, s19, 0x2000
	s_cmpk_lg_i32 s19, 0x4000
	s_cselect_b32 s50, s0, 0
	s_lshl_b32 s0, s38, 1
	v_add_u32_e32 v215, s0, v248
	s_waitcnt vmcnt(3) lgkmcnt(0)
	s_barrier
	s_andn2_b64 vcc, exec, s[78:79]
	v_add_u32_e32 v0, s45, v249
	s_cbranch_vccnz .LBB0_303
	s_waitcnt lgkmcnt(0)
	ds_read_b128 v[100:103], v0 offset:96
	ds_read_b128 v[104:107], v0 offset:64
	ds_read_b128 v[108:111], v0 offset:32
	ds_read_b128 v[112:115], v0
	s_waitcnt lgkmcnt(3)
	v_pk_mul_f32 v[28:29], v[28:29], v[100:101]
	s_waitcnt lgkmcnt(2)
	v_pk_mul_f32 v[24:25], v[24:25], v[104:105]
	s_waitcnt lgkmcnt(1)
	v_pk_mul_f32 v[20:21], v[20:21], v[108:109]
	v_pk_mul_f32 v[30:31], v[30:31], v[102:103]
	v_pk_mul_f32 v[26:27], v[26:27], v[106:107]
	v_pk_mul_f32 v[22:23], v[22:23], v[110:111]
	s_waitcnt lgkmcnt(0)
	v_pk_mul_f32 v[18:19], v[18:19], v[114:115]
	v_pk_mul_f32 v[16:17], v[16:17], v[112:113]
	v_pk_mul_f32 v[44:45], v[44:45], v[100:101]
	v_pk_mul_f32 v[40:41], v[40:41], v[104:105]
	v_pk_mul_f32 v[36:37], v[36:37], v[108:109]
	v_pk_mul_f32 v[46:47], v[46:47], v[102:103]
	v_pk_mul_f32 v[42:43], v[42:43], v[106:107]
	v_pk_mul_f32 v[38:39], v[38:39], v[110:111]
	v_pk_mul_f32 v[34:35], v[34:35], v[114:115]
	v_pk_mul_f32 v[32:33], v[32:33], v[112:113]
	v_pk_mul_f32 v[60:61], v[60:61], v[100:101]
	v_pk_mul_f32 v[56:57], v[56:57], v[104:105]
	v_pk_mul_f32 v[52:53], v[52:53], v[108:109]
	v_pk_mul_f32 v[62:63], v[62:63], v[102:103]
	v_pk_mul_f32 v[58:59], v[58:59], v[106:107]
	v_pk_mul_f32 v[54:55], v[54:55], v[110:111]
	v_pk_mul_f32 v[50:51], v[50:51], v[114:115]
	v_pk_mul_f32 v[48:49], v[48:49], v[112:113]
	v_pk_mul_f32 v[76:77], v[76:77], v[100:101]
	v_pk_mul_f32 v[72:73], v[72:73], v[104:105]
	v_pk_mul_f32 v[68:69], v[68:69], v[108:109]
	v_pk_mul_f32 v[78:79], v[78:79], v[102:103]
	v_pk_mul_f32 v[74:75], v[74:75], v[106:107]
	v_pk_mul_f32 v[70:71], v[70:71], v[110:111]
	v_pk_mul_f32 v[66:67], v[66:67], v[114:115]
	v_pk_mul_f32 v[64:65], v[64:65], v[112:113]
.LBB0_303:
	ds_read_b64_tr_b16 v[192:193], v215 offset:24576
	ds_read_b64_tr_b16 v[194:195], v215 offset:25088
	s_waitcnt lgkmcnt(9)
	v_mfma_f32_32x32x16_bf16 v[112:127], v[96:99], v[188:191], v[80:95]
	v_add_f32_e32 v100, v144, v145
	v_add_f32_e32 v100, v146, v100
	v_add_f32_e32 v100, v147, v100
	v_add_f32_e32 v100, v148, v100
	v_add_f32_e32 v100, v149, v100
	v_cvt_pk_bf16_f32 v180, v144, v145
	v_cvt_pk_bf16_f32 v181, v146, v147
	ds_read_b64_tr_b16 v[144:145], v215 offset:28672
	ds_read_b64_tr_b16 v[146:147], v215 offset:29184
	v_add_f32_e32 v96, v150, v100
	v_add_f32_e32 v96, v151, v96
	v_add_f32_e32 v96, v152, v96
	v_add_f32_e32 v160, v153, v96
	s_waitcnt lgkmcnt(10)
	v_mfma_f32_32x32x16_bf16 v[96:111], v[204:207], v[188:191], v[80:95]
	v_cvt_pk_bf16_f32 v182, v148, v149
	v_cvt_pk_bf16_f32 v183, v150, v151
	ds_read_b64_tr_b16 v[148:149], v215 offset:25600
	ds_read_b64_tr_b16 v[150:151], v215 offset:26112
	s_waitcnt lgkmcnt(11)
	v_mfma_f32_32x32x16_bf16 v[112:127], v[208:211], v[184:187], v[112:127]
	v_add_f32_e32 v160, v154, v160
	v_add_f32_e32 v160, v155, v160
	v_add_f32_e32 v160, v156, v160
	v_add_f32_e32 v160, v157, v160
	v_cvt_pk_bf16_f32 v172, v152, v153
	v_cvt_pk_bf16_f32 v173, v154, v155
	ds_read_b64_tr_b16 v[152:153], v215 offset:29696
	ds_read_b64_tr_b16 v[154:155], v215 offset:30208
	s_waitcnt lgkmcnt(12)
	v_mfma_f32_32x32x16_bf16 v[96:111], v[200:203], v[184:187], v[96:111]
	v_add_f32_e32 v160, v158, v160
	v_add_f32_e32 v160, v159, v160
	v_add_f32_e32 v160, v128, v160
	v_add_f32_e32 v160, v129, v160
	v_cvt_pk_bf16_f32 v174, v156, v157
	v_cvt_pk_bf16_f32 v175, v158, v159
	ds_read_b64_tr_b16 v[156:157], v215 offset:26624
	ds_read_b64_tr_b16 v[158:159], v215 offset:27136
	s_waitcnt lgkmcnt(13)
	v_mfma_f32_32x32x16_bf16 v[112:127], v[196:199], v[176:179], v[112:127]
	v_add_f32_e32 v160, v130, v160
	v_add_f32_e32 v160, v131, v160
	v_add_f32_e32 v160, v132, v160
	v_add_f32_e32 v160, v133, v160
	v_cvt_pk_bf16_f32 v164, v128, v129
	v_cvt_pk_bf16_f32 v165, v130, v131
	ds_read_b64_tr_b16 v[128:129], v215 offset:30720
	ds_read_b64_tr_b16 v[130:131], v215 offset:31232
	s_waitcnt lgkmcnt(14)
	v_mfma_f32_32x32x16_bf16 v[96:111], v[10:13], v[176:179], v[96:111]
	v_add_f32_e32 v10, v134, v160
	v_add_f32_e32 v10, v135, v10
	v_add_f32_e32 v10, v136, v10
	v_add_f32_e32 v160, v137, v10
	v_cvt_pk_bf16_f32 v166, v132, v133
	v_cvt_pk_bf16_f32 v167, v134, v135
	ds_read_b64_tr_b16 v[10:11], v215 offset:27648
	ds_read_b64_tr_b16 v[12:13], v215 offset:28160
	s_waitcnt lgkmcnt(14)
	v_mfma_f32_32x32x16_bf16 v[112:127], v[6:9], v[168:171], v[112:127]
	v_add_f32_e32 v6, v138, v160
	v_add_f32_e32 v6, v139, v6
	v_add_f32_e32 v6, v140, v6
	v_add_f32_e32 v132, v141, v6
	v_cvt_pk_bf16_f32 v160, v136, v137
	v_cvt_pk_bf16_f32 v161, v138, v139
	ds_read_b64_tr_b16 v[6:7], v215 offset:31744
	ds_read_b64_tr_b16 v[8:9], v215 offset:32256
	v_mfma_f32_32x32x16_bf16 v[96:111], v[2:5], v[168:171], v[96:111]
	v_add_f32_e32 v2, v142, v132
	v_add_f32_e32 v2, v143, v2
	v_add_f32_e32 v250, v214, v2
	v_cvt_pk_bf16_f32 v162, v140, v141
	v_cvt_pk_bf16_f32 v163, v142, v143
	s_add_i32 s0, s19, s46
	s_mov_b32 s1, m0
	s_mov_b32 m0, s0
	s_nop 0
	global_load_lds_dwordx4 v253, s[98:99]
	s_mov_b32 m0, s1
	s_waitcnt lgkmcnt(14)
	v_mfma_f32_32x32x16_bf16 v[16:31], v[180:183], v[192:195], v[16:31]
	v_max_f32_e32 v2, v112, v113
	v_max3_f32 v3, v114, v115, v97
	v_max3_f32 v2, v2, v96, v98
	v_max3_f32 v2, v2, v99, v116
	v_max3_f32 v3, v3, v118, v119
	v_max3_f32 v2, v2, v117, v100
	s_waitcnt lgkmcnt(12)
	v_mfma_f32_32x32x16_bf16 v[32:47], v[180:183], v[144:147], v[32:47]
	v_max3_f32 v3, v3, v102, v103
	v_max3_f32 v2, v2, v101, v120
	v_max3_f32 v3, v3, v122, v123
	v_max3_f32 v2, v2, v121, v104
	v_max3_f32 v3, v3, v106, v107
	v_max3_f32 v2, v2, v105, v124
	s_waitcnt lgkmcnt(10)
	v_mfma_f32_32x32x16_bf16 v[16:31], v[172:175], v[148:151], v[16:31]
	v_max3_f32 v3, v3, v126, v127
	v_max3_f32 v2, v2, v125, v108
	v_max3_f32 v3, v3, v110, v111
	v_max3_f32 v2, v2, v109, v3
	v_mov_b32_e32 v3, v2
	s_nop 1
	v_permlane32_swap_b32_e32 v2, v3
	v_max_f32_e32 v2, v2, v3
	v_cmp_lt_f32_e32 vcc, s25, v2
	s_cmp_lg_u64 vcc, 0
	s_cselect_b64 s[78:79], -1, 0
	s_cbranch_vccnz .LBB0_311
.LBB0_304:
	v_exp_f32_e32 v112, v112
	v_exp_f32_e32 v113, v113
	ds_read_b64_tr_b16 v[2:3], v215 offset:32768
	ds_read_b64_tr_b16 v[4:5], v215 offset:33280
	v_exp_f32_e32 v114, v114
	v_exp_f32_e32 v115, v115
	ds_read_b64_tr_b16 v[132:133], v215 offset:36864
	ds_read_b64_tr_b16 v[134:135], v215 offset:37376
	s_lshl_b32 s0, s50, 1
	s_add_i32 s18, s0, s47
	s_mov_b32 s0, m0
	s_mov_b32 m0, s18
	s_nop 0
	global_load_lds_dwordx4 v255, s[100:101]
	s_mov_b32 m0, s0
	v_exp_f32_e32 v116, v116
	v_exp_f32_e32 v117, v117
	ds_read_b64_tr_b16 v[136:137], v215 offset:33792
	ds_read_b64_tr_b16 v[138:139], v215 offset:34304
	s_add_i32 s0, s18, 0x1f80
	s_mov_b32 s1, m0
	s_mov_b32 m0, s0
	s_nop 0
	global_load_lds_dwordx4 v255, s[100:101] offset:128
	s_mov_b32 m0, s1
	s_add_u32 s98, s98, 0x20000
	s_addc_u32 s99, s99, 0
	s_add_u32 s100, s100, 0x20000
	s_addc_u32 s101, s101, 0
	s_waitcnt lgkmcnt(14)
	v_mfma_f32_32x32x16_bf16 v[32:47], v[172:175], v[152:155], v[32:47]
	v_exp_f32_e32 v118, v118
	v_exp_f32_e32 v119, v119
	ds_read_b64_tr_b16 v[140:141], v215 offset:37888
	ds_read_b64_tr_b16 v[142:143], v215 offset:38400
	s_waitcnt lgkmcnt(14)
	v_mfma_f32_32x32x16_bf16 v[16:31], v[164:167], v[156:159], v[16:31]
	v_exp_f32_e32 v120, v120
	v_exp_f32_e32 v121, v121
	ds_read_b64_tr_b16 v[144:145], v215 offset:34816
	ds_read_b64_tr_b16 v[146:147], v215 offset:35328
	s_waitcnt lgkmcnt(14)
	v_mfma_f32_32x32x16_bf16 v[32:47], v[164:167], v[128:131], v[32:47]
	v_exp_f32_e32 v122, v122
	v_exp_f32_e32 v123, v123
	ds_read_b64_tr_b16 v[128:129], v215 offset:38912
	ds_read_b64_tr_b16 v[130:131], v215 offset:39424
	s_waitcnt lgkmcnt(14)
	v_mfma_f32_32x32x16_bf16 v[16:31], v[160:163], v[10:13], v[16:31]
	v_exp_f32_e32 v124, v124
	v_exp_f32_e32 v125, v125
	ds_read_b64_tr_b16 v[10:11], v215 offset:35840
	ds_read_b64_tr_b16 v[12:13], v215 offset:36352
	s_waitcnt lgkmcnt(14)
	v_mfma_f32_32x32x16_bf16 v[32:47], v[160:163], v[6:9], v[32:47]
	v_exp_f32_e32 v126, v126
	v_exp_f32_e32 v127, v127
	ds_read_b64_tr_b16 v[6:7], v215 offset:39936
	ds_read_b64_tr_b16 v[8:9], v215 offset:40448
	s_waitcnt lgkmcnt(14)
	v_mfma_f32_32x32x16_bf16 v[48:63], v[180:183], v[2:5], v[48:63]
	v_exp_f32_e32 v96, v96
	v_exp_f32_e32 v97, v97
	s_waitcnt lgkmcnt(12)
	v_mfma_f32_32x32x16_bf16 v[64:79], v[180:183], v[132:135], v[64:79]
	v_exp_f32_e32 v98, v98
	v_exp_f32_e32 v99, v99
	v_add_u32_e32 v2, s50, v247
	ds_read_b128 v[220:223], v2
	ds_read_b128 v[216:219], v2 offset:512
	s_waitcnt lgkmcnt(12)
	v_mfma_f32_32x32x16_bf16 v[48:63], v[172:175], v[136:139], v[48:63]
	v_exp_f32_e32 v100, v100
	v_exp_f32_e32 v101, v101
	ds_read_b128 v[212:215], v2 offset:2048
	ds_read_b128 v[208:211], v2 offset:2560
	s_waitcnt lgkmcnt(12)
	v_mfma_f32_32x32x16_bf16 v[64:79], v[172:175], v[140:143], v[64:79]
	v_exp_f32_e32 v102, v102
	v_exp_f32_e32 v103, v103
	ds_read_b128 v[204:207], v2 offset:4096
	ds_read_b128 v[200:203], v2 offset:4608
	s_waitcnt lgkmcnt(12)
	v_mfma_f32_32x32x16_bf16 v[48:63], v[164:167], v[144:147], v[48:63]
	v_exp_f32_e32 v104, v104
	v_exp_f32_e32 v105, v105
	ds_read_b128 v[196:199], v2 offset:6144
	ds_read_b128 v[192:195], v2 offset:6656
	s_waitcnt lgkmcnt(12)
	v_mfma_f32_32x32x16_bf16 v[64:79], v[164:167], v[128:131], v[64:79]
	v_exp_f32_e32 v106, v106
	v_exp_f32_e32 v107, v107
	s_waitcnt lgkmcnt(10)
	v_mfma_f32_32x32x16_bf16 v[48:63], v[160:163], v[10:13], v[48:63]
	v_exp_f32_e32 v108, v108
	v_exp_f32_e32 v109, v109
	s_waitcnt lgkmcnt(8)
	v_mfma_f32_32x32x16_bf16 v[64:79], v[160:163], v[6:9], v[64:79]
	v_exp_f32_e32 v110, v110
	v_exp_f32_e32 v111, v111
	s_add_i32 s6, s6, 2
	s_add_i32 s0, s50, 0x2000
	s_cmpk_lg_i32 s50, 0x4000
	s_cselect_b32 s18, s0, 0
	s_mov_b32 s0, s19
	s_mov_b32 s38, s50
	s_mov_b32 s19, s18
	s_waitcnt vmcnt(3) lgkmcnt(0)
	s_barrier
	s_andn2_b64 vcc, exec, s[78:79]
	s_cbranch_vccnz .LBB0_306
	s_waitcnt lgkmcnt(0)
	ds_read_b128 v[2:5], v0 offset:96
	ds_read_b128 v[6:9], v0 offset:64
	ds_read_b128 v[10:13], v0 offset:32
	ds_read_b128 v[128:131], v0
	s_waitcnt lgkmcnt(3)
	v_pk_mul_f32 v[28:29], v[28:29], v[2:3]
	s_waitcnt lgkmcnt(2)
	v_pk_mul_f32 v[24:25], v[24:25], v[6:7]
	s_waitcnt lgkmcnt(1)
	v_pk_mul_f32 v[20:21], v[20:21], v[10:11]
	v_pk_mul_f32 v[30:31], v[30:31], v[4:5]
	v_pk_mul_f32 v[26:27], v[26:27], v[8:9]
	v_pk_mul_f32 v[22:23], v[22:23], v[12:13]
	s_waitcnt lgkmcnt(0)
	v_pk_mul_f32 v[18:19], v[18:19], v[130:131]
	v_pk_mul_f32 v[16:17], v[16:17], v[128:129]
	v_pk_mul_f32 v[44:45], v[44:45], v[2:3]
	v_pk_mul_f32 v[40:41], v[40:41], v[6:7]
	v_pk_mul_f32 v[36:37], v[36:37], v[10:11]
	v_pk_mul_f32 v[46:47], v[46:47], v[4:5]
	v_pk_mul_f32 v[42:43], v[42:43], v[8:9]
	v_pk_mul_f32 v[38:39], v[38:39], v[12:13]
	v_pk_mul_f32 v[34:35], v[34:35], v[130:131]
	v_pk_mul_f32 v[32:33], v[32:33], v[128:129]
	v_pk_mul_f32 v[60:61], v[60:61], v[2:3]
	v_pk_mul_f32 v[56:57], v[56:57], v[6:7]
	v_pk_mul_f32 v[52:53], v[52:53], v[10:11]
	v_pk_mul_f32 v[62:63], v[62:63], v[4:5]
	v_pk_mul_f32 v[58:59], v[58:59], v[8:9]
	v_pk_mul_f32 v[54:55], v[54:55], v[12:13]
	v_pk_mul_f32 v[50:51], v[50:51], v[130:131]
	v_pk_mul_f32 v[48:49], v[48:49], v[128:129]
	v_pk_mul_f32 v[76:77], v[76:77], v[2:3]
	v_pk_mul_f32 v[72:73], v[72:73], v[6:7]
	v_pk_mul_f32 v[68:69], v[68:69], v[10:11]
	v_pk_mul_f32 v[78:79], v[78:79], v[4:5]
	v_pk_mul_f32 v[74:75], v[74:75], v[8:9]
	v_pk_mul_f32 v[70:71], v[70:71], v[12:13]
	v_pk_mul_f32 v[66:67], v[66:67], v[130:131]
	v_pk_mul_f32 v[64:65], v[64:65], v[128:129]
.LBB0_306:
	s_cmp_lt_i32 s6, s26
	s_cbranch_scc1 .LBB0_300
	s_mov_b32 s19, s0
	s_branch .LBB0_315
